# attnA: first three V^T fragment reads of the PV block issued in the QK tail (into retiring K ring buffers)
# speedup vs baseline: 1.0098x; 1.0007x over previous
.LBB0_1369:
	s_or_b32 s82, s34, 1
	s_lshl_b64 s[4:5], s[82:83], 7
	s_add_u32 s4, s8, s4
	s_addc_u32 s5, s9, s5
	s_add_u32 m0, s38, 0x8000
	s_nop 0
	global_load_lds_dwordx4 v198, s[4:5]
	s_add_u32 m0, s38, 0x9000
	s_nop 0
	global_load_lds_dwordx4 v199, s[4:5]
	s_add_u32 m0, s38, 0xa000
	s_nop 0
	global_load_lds_dwordx4 v200, s[4:5]
	s_add_u32 m0, s38, 0xb000
	s_nop 0
	global_load_lds_dwordx4 v201, s[4:5]
	v_cmp_lt_i32_e64 s[4:5], s34, v226
	s_and_saveexec_b64 s[22:23], s[4:5]
	s_cbranch_execz .LBB0_1371
	ds_read_b128 v[2:5], v222 offset:24576
	ds_read_b128 v[6:9], v222 offset:28672
	ds_read_b128 v[10:13], v223 offset:24576
	ds_read_b128 v[244:247], v223 offset:28672
	s_waitcnt lgkmcnt(3)
	v_mfma_f32_32x32x16_bf16 v[128:143], v[2:5], v[160:163], v[16:31]
	v_exp_f32_e32 v32, v32
	v_exp_f32_e32 v33, v33
	ds_read_b128 v[2:5], v224 offset:24576
	s_waitcnt lgkmcnt(3)
	v_mfma_f32_32x32x16_bf16 v[144:159], v[6:9], v[160:163], v[16:31]
	v_exp_f32_e32 v34, v34
	v_exp_f32_e32 v35, v35
	ds_read_b128 v[6:9], v224 offset:28672
	s_waitcnt lgkmcnt(3)
	v_mfma_f32_32x32x16_bf16 v[128:143], v[10:13], v[164:167], v[128:143]
	v_exp_f32_e32 v36, v36
	v_exp_f32_e32 v37, v37
	v_add_f32_e32 v0, 0, v32
	ds_read_b128 v[10:13], v225 offset:24576
	s_waitcnt lgkmcnt(3)
	v_mfma_f32_32x32x16_bf16 v[144:159], v[244:247], v[164:167], v[144:159]
	v_exp_f32_e32 v38, v38
	v_exp_f32_e32 v39, v39
	v_add_f32_e32 v0, v33, v0
	ds_read_b128 v[244:247], v225 offset:28672
	s_waitcnt lgkmcnt(3)
	v_mfma_f32_32x32x16_bf16 v[128:143], v[2:5], v[168:171], v[128:143]
	v_cvt_pk_bf16_f32 v208, v32, v33
	v_add_f32_e32 v0, v34, v0
	v_add_f32_e32 v0, v35, v0
	s_waitcnt lgkmcnt(2)
	v_mfma_f32_32x32x16_bf16 v[144:159], v[6:9], v[168:171], v[144:159]
	v_cvt_pk_bf16_f32 v209, v34, v35
	v_add_f32_e32 v0, v36, v0
	v_add_f32_e32 v0, v37, v0
	ds_read_b64 v[6:7], v228 offset:8192
	ds_read_b64 v[8:9], v229 offset:8192
	s_waitcnt lgkmcnt(3)
	v_mfma_f32_32x32x16_bf16 v[128:143], v[10:13], v[172:175], v[128:143]
	v_cvt_pk_bf16_f32 v210, v36, v37
	v_add_f32_e32 v0, v38, v0
	ds_read_b64 v[10:11], v230 offset:20480
	ds_read_b64 v[12:13], v231 offset:20480
	s_waitcnt lgkmcnt(4)
	v_mfma_f32_32x32x16_bf16 v[144:159], v[244:247], v[172:175], v[144:159]
	v_cvt_pk_bf16_f32 v211, v38, v39
	v_add_f32_e32 v0, v39, v0
	ds_read_b64 v[244:245], v230 offset:12288
	ds_read_b64 v[246:247], v231 offset:12288
	s_or_b64 exec, exec, s[22:23]
	v_cmp_le_i32_e32 vcc, s34, v226
	s_and_saveexec_b64 s[22:23], vcc
	ds_read_b64 v[32:33], v230 offset:16384
	ds_read_b64 v[34:35], v231 offset:16384
	ds_read_b64 v[36:37], v232 offset:8192
	ds_read_b64 v[38:39], v233 offset:8192
	s_waitcnt lgkmcnt(8)
	v_mfma_f32_32x32x16_bf16 v[112:127], v[6:9], v[208:211], v[112:127]
	ds_read_b64 v[6:7], v234 offset:20480
	ds_read_b64 v[8:9], v235 offset:20480
	v_exp_f32_e32 v40, v40
	v_exp_f32_e32 v41, v41
	s_waitcnt lgkmcnt(8)
	v_mfma_f32_32x32x16_bf16 v[64:79], v[10:13], v[208:211], v[64:79]
	ds_read_b64 v[10:11], v234 offset:12288
	ds_read_b64 v[12:13], v235 offset:12288
	v_exp_f32_e32 v42, v42
	v_exp_f32_e32 v43, v43
	v_add_f32_e32 v0, v40, v0
	v_add_f32_e32 v0, v41, v0
	s_waitcnt lgkmcnt(8)
	v_mfma_f32_32x32x16_bf16 v[96:111], v[244:247], v[208:211], v[96:111]
	ds_read_b64 v[244:245], v234 offset:16384
	ds_read_b64 v[246:247], v235 offset:16384
	v_exp_f32_e32 v44, v44
	v_exp_f32_e32 v45, v45
	v_add_f32_e32 v0, v42, v0
	v_add_f32_e32 v0, v43, v0
	s_waitcnt lgkmcnt(8)
	v_mfma_f32_32x32x16_bf16 v[80:95], v[32:35], v[208:211], v[80:95]
	ds_read_b64 v[32:33], v236 offset:8192
	ds_read_b64 v[34:35], v237 offset:8192
	v_exp_f32_e32 v46, v46
	v_exp_f32_e32 v47, v47
	v_add_f32_e32 v0, v44, v0
	v_add_f32_e32 v0, v45, v0
	v_add_f32_e32 v0, v46, v0
	v_add_f32_e32 v0, v47, v0
	v_cvt_pk_bf16_f32 v2, v40, v41
	v_cvt_pk_bf16_f32 v3, v42, v43
	v_cvt_pk_bf16_f32 v4, v44, v45
	v_cvt_pk_bf16_f32 v5, v46, v47
	s_nop 1
	ds_read_b64 v[40:41], v238 offset:20480
	ds_read_b64 v[42:43], v239 offset:20480
	s_waitcnt lgkmcnt(10)
	v_mfma_f32_32x32x16_bf16 v[112:127], v[36:39], v[2:5], v[112:127]
	ds_read_b64 v[44:45], v238 offset:12288
	ds_read_b64 v[46:47], v239 offset:12288
	v_exp_f32_e32 v48, v48
	v_exp_f32_e32 v49, v49
	s_waitcnt lgkmcnt(10)
	v_mfma_f32_32x32x16_bf16 v[64:79], v[6:9], v[2:5], v[64:79]
	ds_read_b64 v[36:37], v238 offset:16384
	ds_read_b64 v[38:39], v239 offset:16384
	v_exp_f32_e32 v50, v50
	v_exp_f32_e32 v51, v51
	v_add_f32_e32 v0, v48, v0
	v_add_f32_e32 v0, v49, v0
	s_waitcnt lgkmcnt(10)
	v_mfma_f32_32x32x16_bf16 v[96:111], v[10:13], v[2:5], v[96:111]
	ds_read_b64 v[6:7], v240 offset:8192
	ds_read_b64 v[8:9], v241 offset:8192
	v_exp_f32_e32 v52, v52
	v_exp_f32_e32 v53, v53
	v_add_f32_e32 v0, v50, v0
	v_add_f32_e32 v0, v51, v0
	s_waitcnt lgkmcnt(10)
	v_mfma_f32_32x32x16_bf16 v[80:95], v[244:247], v[2:5], v[80:95]
	ds_read_b64 v[10:11], v242 offset:12288
	ds_read_b64 v[12:13], v243 offset:12288
	v_exp_f32_e32 v54, v54
	v_exp_f32_e32 v55, v55
	v_add_f32_e32 v0, v52, v0
	v_add_f32_e32 v0, v53, v0
	v_add_f32_e32 v0, v54, v0
	v_add_f32_e32 v0, v55, v0
	v_cvt_pk_bf16_f32 v2, v48, v49
	v_cvt_pk_bf16_f32 v3, v50, v51
	v_cvt_pk_bf16_f32 v4, v52, v53
	v_cvt_pk_bf16_f32 v5, v54, v55
	s_nop 1
	ds_read_b64 v[244:245], v242 offset:16384
	ds_read_b64 v[246:247], v243 offset:16384
	s_waitcnt lgkmcnt(12)
	v_mfma_f32_32x32x16_bf16 v[112:127], v[32:35], v[2:5], v[112:127]
	ds_read_b64 v[48:49], v242 offset:20480
	ds_read_b64 v[50:51], v243 offset:20480
	v_exp_f32_e32 v56, v56
	v_exp_f32_e32 v57, v57
	s_waitcnt lgkmcnt(12)
	v_mfma_f32_32x32x16_bf16 v[64:79], v[40:43], v[2:5], v[64:79]
	v_exp_f32_e32 v58, v58
	v_exp_f32_e32 v59, v59
	v_add_f32_e32 v0, v56, v0
	v_add_f32_e32 v0, v57, v0
	s_waitcnt lgkmcnt(10)
	v_mfma_f32_32x32x16_bf16 v[96:111], v[44:47], v[2:5], v[96:111]
	v_exp_f32_e32 v60, v60
	v_exp_f32_e32 v61, v61
	v_add_f32_e32 v0, v58, v0
	v_add_f32_e32 v0, v59, v0
	s_waitcnt lgkmcnt(8)
	v_mfma_f32_32x32x16_bf16 v[80:95], v[36:39], v[2:5], v[80:95]
	v_exp_f32_e32 v62, v62
	v_exp_f32_e32 v63, v63
	v_add_f32_e32 v0, v60, v0
	v_add_f32_e32 v0, v61, v0
	v_add_f32_e32 v0, v62, v0
	v_add_f32_e32 v0, v63, v0
	v_cvt_pk_bf16_f32 v2, v56, v57
	v_cvt_pk_bf16_f32 v3, v58, v59
	v_cvt_pk_bf16_f32 v4, v60, v61
	v_cvt_pk_bf16_f32 v5, v62, v63
	s_nop 1
	s_waitcnt lgkmcnt(6)
	v_mfma_f32_32x32x16_bf16 v[112:127], v[6:9], v[2:5], v[112:127]
	s_waitcnt lgkmcnt(4)
	v_mfma_f32_32x32x16_bf16 v[96:111], v[10:13], v[2:5], v[96:111]
	s_waitcnt lgkmcnt(2)
	v_mfma_f32_32x32x16_bf16 v[80:95], v[244:247], v[2:5], v[80:95]
	s_waitcnt lgkmcnt(0)
	v_mfma_f32_32x32x16_bf16 v[64:79], v[48:51], v[2:5], v[64:79]
	v_add_f32_e32 v227, v227, v0
	s_branch .LBB0_1373

.LBB0_1381:
	ds_read_b128 v[2:5], v222
	ds_read_b128 v[6:9], v222 offset:4096
	ds_read_b128 v[10:13], v223
	ds_read_b128 v[244:247], v223 offset:4096
	s_waitcnt lgkmcnt(3)
	v_mfma_f32_32x32x16_bf16 v[32:47], v[2:5], v[160:163], v[16:31]
	v_exp_f32_e32 v128, v128
	v_exp_f32_e32 v129, v129
	ds_read_b128 v[2:5], v224
	s_waitcnt lgkmcnt(3)
	v_mfma_f32_32x32x16_bf16 v[48:63], v[6:9], v[160:163], v[16:31]
	v_exp_f32_e32 v130, v130
	v_exp_f32_e32 v131, v131
	ds_read_b128 v[6:9], v224 offset:4096
	s_waitcnt lgkmcnt(3)
	v_mfma_f32_32x32x16_bf16 v[32:47], v[10:13], v[164:167], v[32:47]
	v_exp_f32_e32 v132, v132
	v_exp_f32_e32 v133, v133
	v_add_f32_e32 v0, 0, v128
	ds_read_b128 v[10:13], v225
	s_waitcnt lgkmcnt(3)
	v_mfma_f32_32x32x16_bf16 v[48:63], v[244:247], v[164:167], v[48:63]
	v_exp_f32_e32 v134, v134
	v_exp_f32_e32 v135, v135
	v_add_f32_e32 v0, v129, v0
	ds_read_b128 v[244:247], v225 offset:4096
	s_waitcnt lgkmcnt(3)
	v_mfma_f32_32x32x16_bf16 v[32:47], v[2:5], v[168:171], v[32:47]
	v_cvt_pk_bf16_f32 v208, v128, v129
	v_add_f32_e32 v0, v130, v0
	v_add_f32_e32 v0, v131, v0
	s_waitcnt lgkmcnt(2)
	v_mfma_f32_32x32x16_bf16 v[48:63], v[6:9], v[168:171], v[48:63]
	v_cvt_pk_bf16_f32 v209, v130, v131
	v_add_f32_e32 v0, v132, v0
	v_add_f32_e32 v0, v133, v0
	ds_read_b64 v[6:7], v228 offset:32768
	ds_read_b64 v[8:9], v229 offset:32768
	s_waitcnt lgkmcnt(3)
	v_mfma_f32_32x32x16_bf16 v[32:47], v[10:13], v[172:175], v[32:47]
	v_cvt_pk_bf16_f32 v210, v132, v133
	v_add_f32_e32 v0, v134, v0
	ds_read_b64 v[10:11], v230 offset:45056
	ds_read_b64 v[12:13], v231 offset:45056
	s_waitcnt lgkmcnt(4)
	v_mfma_f32_32x32x16_bf16 v[48:63], v[244:247], v[172:175], v[48:63]
	v_cvt_pk_bf16_f32 v211, v134, v135
	v_add_f32_e32 v0, v135, v0
	ds_read_b64 v[244:245], v230 offset:36864
	ds_read_b64 v[246:247], v231 offset:36864
	s_or_b64 exec, exec, s[20:21]
	s_and_saveexec_b64 s[20:21], s[4:5]
	ds_read_b64 v[128:129], v230 offset:40960
	ds_read_b64 v[130:131], v231 offset:40960
	ds_read_b64 v[132:133], v232 offset:32768
	ds_read_b64 v[134:135], v233 offset:32768
	s_waitcnt lgkmcnt(8)
	v_mfma_f32_32x32x16_bf16 v[112:127], v[6:9], v[208:211], v[112:127]
	ds_read_b64 v[6:7], v234 offset:45056
	ds_read_b64 v[8:9], v235 offset:45056
	v_exp_f32_e32 v136, v136
	v_exp_f32_e32 v137, v137
	s_waitcnt lgkmcnt(8)
	v_mfma_f32_32x32x16_bf16 v[64:79], v[10:13], v[208:211], v[64:79]
	ds_read_b64 v[10:11], v234 offset:36864
	ds_read_b64 v[12:13], v235 offset:36864
	v_exp_f32_e32 v138, v138
	v_exp_f32_e32 v139, v139
	v_add_f32_e32 v0, v136, v0
	v_add_f32_e32 v0, v137, v0
	s_waitcnt lgkmcnt(8)
	v_mfma_f32_32x32x16_bf16 v[96:111], v[244:247], v[208:211], v[96:111]
	ds_read_b64 v[244:245], v234 offset:40960
	ds_read_b64 v[246:247], v235 offset:40960
	v_exp_f32_e32 v140, v140
	v_exp_f32_e32 v141, v141
	v_add_f32_e32 v0, v138, v0
	v_add_f32_e32 v0, v139, v0
	s_waitcnt lgkmcnt(8)
	v_mfma_f32_32x32x16_bf16 v[80:95], v[128:131], v[208:211], v[80:95]
	ds_read_b64 v[128:129], v236 offset:32768
	ds_read_b64 v[130:131], v237 offset:32768
	v_exp_f32_e32 v142, v142
	v_exp_f32_e32 v143, v143
	v_add_f32_e32 v0, v140, v0
	v_add_f32_e32 v0, v141, v0
	v_add_f32_e32 v0, v142, v0
	v_add_f32_e32 v0, v143, v0
	v_cvt_pk_bf16_f32 v2, v136, v137
	v_cvt_pk_bf16_f32 v3, v138, v139
	v_cvt_pk_bf16_f32 v4, v140, v141
	v_cvt_pk_bf16_f32 v5, v142, v143
	s_nop 1
	ds_read_b64 v[136:137], v238 offset:45056
	ds_read_b64 v[138:139], v239 offset:45056
	s_waitcnt lgkmcnt(10)
	v_mfma_f32_32x32x16_bf16 v[112:127], v[132:135], v[2:5], v[112:127]
	ds_read_b64 v[140:141], v238 offset:36864
	ds_read_b64 v[142:143], v239 offset:36864
	v_exp_f32_e32 v144, v144
	v_exp_f32_e32 v145, v145
	s_waitcnt lgkmcnt(10)
	v_mfma_f32_32x32x16_bf16 v[64:79], v[6:9], v[2:5], v[64:79]
	ds_read_b64 v[132:133], v238 offset:40960
	ds_read_b64 v[134:135], v239 offset:40960
	v_exp_f32_e32 v146, v146
	v_exp_f32_e32 v147, v147
	v_add_f32_e32 v0, v144, v0
	v_add_f32_e32 v0, v145, v0
	s_waitcnt lgkmcnt(10)
	v_mfma_f32_32x32x16_bf16 v[96:111], v[10:13], v[2:5], v[96:111]
	ds_read_b64 v[6:7], v240 offset:32768
	ds_read_b64 v[8:9], v241 offset:32768
	v_exp_f32_e32 v148, v148
	v_exp_f32_e32 v149, v149
	v_add_f32_e32 v0, v146, v0
	v_add_f32_e32 v0, v147, v0
	s_waitcnt lgkmcnt(10)
	v_mfma_f32_32x32x16_bf16 v[80:95], v[244:247], v[2:5], v[80:95]
	ds_read_b64 v[10:11], v242 offset:36864
	ds_read_b64 v[12:13], v243 offset:36864
	v_exp_f32_e32 v150, v150
	v_exp_f32_e32 v151, v151
	v_add_f32_e32 v0, v148, v0
	v_add_f32_e32 v0, v149, v0
	v_add_f32_e32 v0, v150, v0
	v_add_f32_e32 v0, v151, v0
	v_cvt_pk_bf16_f32 v2, v144, v145
	v_cvt_pk_bf16_f32 v3, v146, v147
	v_cvt_pk_bf16_f32 v4, v148, v149
	v_cvt_pk_bf16_f32 v5, v150, v151
	s_nop 1
	ds_read_b64 v[244:245], v242 offset:40960
	ds_read_b64 v[246:247], v243 offset:40960
	s_waitcnt lgkmcnt(12)
	v_mfma_f32_32x32x16_bf16 v[112:127], v[128:131], v[2:5], v[112:127]
	ds_read_b64 v[144:145], v242 offset:45056
	ds_read_b64 v[146:147], v243 offset:45056
	v_exp_f32_e32 v152, v152
	v_exp_f32_e32 v153, v153
	s_waitcnt lgkmcnt(12)
	v_mfma_f32_32x32x16_bf16 v[64:79], v[136:139], v[2:5], v[64:79]
	v_exp_f32_e32 v154, v154
	v_exp_f32_e32 v155, v155
	v_add_f32_e32 v0, v152, v0
	v_add_f32_e32 v0, v153, v0
	s_waitcnt lgkmcnt(10)
	v_mfma_f32_32x32x16_bf16 v[96:111], v[140:143], v[2:5], v[96:111]
	v_exp_f32_e32 v156, v156
	v_exp_f32_e32 v157, v157
	v_add_f32_e32 v0, v154, v0
	v_add_f32_e32 v0, v155, v0
	s_waitcnt lgkmcnt(8)
	v_mfma_f32_32x32x16_bf16 v[80:95], v[132:135], v[2:5], v[80:95]
	v_exp_f32_e32 v158, v158
	v_exp_f32_e32 v159, v159
	v_add_f32_e32 v0, v156, v0
	v_add_f32_e32 v0, v157, v0
	v_add_f32_e32 v0, v158, v0
	v_add_f32_e32 v0, v159, v0
	v_cvt_pk_bf16_f32 v2, v152, v153
	v_cvt_pk_bf16_f32 v3, v154, v155
	v_cvt_pk_bf16_f32 v4, v156, v157
	v_cvt_pk_bf16_f32 v5, v158, v159
	s_nop 1
	s_waitcnt lgkmcnt(6)
	v_mfma_f32_32x32x16_bf16 v[112:127], v[6:9], v[2:5], v[112:127]
	s_waitcnt lgkmcnt(4)
	v_mfma_f32_32x32x16_bf16 v[96:111], v[10:13], v[2:5], v[96:111]
	s_waitcnt lgkmcnt(2)
	v_mfma_f32_32x32x16_bf16 v[80:95], v[244:247], v[2:5], v[80:95]
	s_waitcnt lgkmcnt(0)
	v_mfma_f32_32x32x16_bf16 v[64:79], v[144:147], v[2:5], v[64:79]
	v_add_f32_e32 v227, v0, v227
	s_branch .LBB0_1386

.LBB0_1411:
	s_or_b32 s82, s31, 1
	s_lshl_b64 s[4:5], s[82:83], 7
	s_add_u32 s4, s8, s4
	s_addc_u32 s5, s9, s5
	s_add_u32 m0, s38, 0x8000
	s_nop 0
	global_load_lds_dwordx4 v196, s[4:5]
	s_add_u32 m0, s38, 0x9000
	s_nop 0
	global_load_lds_dwordx4 v197, s[4:5]
	s_add_u32 m0, s38, 0xa000
	s_nop 0
	global_load_lds_dwordx4 v198, s[4:5]
	s_add_u32 m0, s38, 0xb000
	s_nop 0
	global_load_lds_dwordx4 v199, s[4:5]
	v_cmp_lt_i32_e64 s[4:5], s31, v225
	s_and_saveexec_b64 s[22:23], s[4:5]
	s_cbranch_execz .LBB0_1413
	ds_read_b128 v[2:5], v220 offset:24576
	ds_read_b128 v[6:9], v220 offset:28672
	ds_read_b128 v[10:13], v221 offset:24576
	ds_read_b128 v[244:247], v221 offset:28672
	s_waitcnt lgkmcnt(3)
	v_mfma_f32_32x32x16_bf16 v[128:143], v[2:5], v[160:163], v[16:31]
	v_exp_f32_e32 v80, v80
	v_exp_f32_e32 v81, v81
	ds_read_b128 v[2:5], v222 offset:24576
	s_waitcnt lgkmcnt(3)
	v_mfma_f32_32x32x16_bf16 v[144:159], v[6:9], v[160:163], v[16:31]
	v_exp_f32_e32 v82, v82
	v_exp_f32_e32 v83, v83
	ds_read_b128 v[6:9], v222 offset:28672
	s_waitcnt lgkmcnt(3)
	v_mfma_f32_32x32x16_bf16 v[128:143], v[10:13], v[164:167], v[128:143]
	v_exp_f32_e32 v84, v84
	v_exp_f32_e32 v85, v85
	v_add_f32_e32 v0, 0, v80
	ds_read_b128 v[10:13], v223 offset:24576
	s_waitcnt lgkmcnt(3)
	v_mfma_f32_32x32x16_bf16 v[144:159], v[244:247], v[164:167], v[144:159]
	v_exp_f32_e32 v86, v86
	v_exp_f32_e32 v87, v87
	v_add_f32_e32 v0, v81, v0
	ds_read_b128 v[244:247], v223 offset:28672
	s_waitcnt lgkmcnt(3)
	v_mfma_f32_32x32x16_bf16 v[128:143], v[2:5], v[168:171], v[128:143]
	v_cvt_pk_bf16_f32 v208, v80, v81
	v_add_f32_e32 v0, v82, v0
	v_add_f32_e32 v0, v83, v0
	s_waitcnt lgkmcnt(2)
	v_mfma_f32_32x32x16_bf16 v[144:159], v[6:9], v[168:171], v[144:159]
	v_cvt_pk_bf16_f32 v209, v82, v83
	v_add_f32_e32 v0, v84, v0
	v_add_f32_e32 v0, v85, v0
	ds_read_b64 v[6:7], v226 offset:8192
	ds_read_b64 v[8:9], v227 offset:8192
	s_waitcnt lgkmcnt(3)
	v_mfma_f32_32x32x16_bf16 v[128:143], v[10:13], v[172:175], v[128:143]
	v_cvt_pk_bf16_f32 v210, v84, v85
	v_add_f32_e32 v0, v86, v0
	ds_read_b64 v[10:11], v228 offset:20480
	ds_read_b64 v[12:13], v229 offset:20480
	s_waitcnt lgkmcnt(4)
	v_mfma_f32_32x32x16_bf16 v[144:159], v[244:247], v[172:175], v[144:159]
	v_cvt_pk_bf16_f32 v211, v86, v87
	v_add_f32_e32 v0, v87, v0
	ds_read_b64 v[242:243], v228 offset:12288
	ds_read_b64 v[244:245], v229 offset:12288
	s_or_b64 exec, exec, s[22:23]
	v_cmp_le_i32_e32 vcc, s31, v225
	s_and_saveexec_b64 s[22:23], vcc
	ds_read_b64 v[80:81], v228 offset:16384
	ds_read_b64 v[82:83], v229 offset:16384
	ds_read_b64 v[84:85], v230 offset:8192
	ds_read_b64 v[86:87], v231 offset:8192
	s_waitcnt lgkmcnt(8)
	v_mfma_f32_32x32x16_bf16 v[64:79], v[6:9], v[208:211], v[64:79]
	ds_read_b64 v[6:7], v232 offset:20480
	ds_read_b64 v[8:9], v233 offset:20480
	v_exp_f32_e32 v88, v88
	v_exp_f32_e32 v89, v89
	s_waitcnt lgkmcnt(8)
	v_mfma_f32_32x32x16_bf16 v[112:127], v[10:13], v[208:211], v[112:127]
	ds_read_b64 v[10:11], v232 offset:12288
	ds_read_b64 v[12:13], v233 offset:12288
	v_exp_f32_e32 v90, v90
	v_exp_f32_e32 v91, v91
	v_add_f32_e32 v0, v88, v0
	v_add_f32_e32 v0, v89, v0
	s_waitcnt lgkmcnt(8)
	v_mfma_f32_32x32x16_bf16 v[48:63], v[242:245], v[208:211], v[48:63]
	ds_read_b64 v[242:243], v232 offset:16384
	ds_read_b64 v[244:245], v233 offset:16384
	v_exp_f32_e32 v92, v92
	v_exp_f32_e32 v93, v93
	v_add_f32_e32 v0, v90, v0
	v_add_f32_e32 v0, v91, v0
	s_waitcnt lgkmcnt(8)
	v_mfma_f32_32x32x16_bf16 v[32:47], v[80:83], v[208:211], v[32:47]
	ds_read_b64 v[80:81], v234 offset:8192
	ds_read_b64 v[82:83], v235 offset:8192
	v_exp_f32_e32 v94, v94
	v_exp_f32_e32 v95, v95
	v_add_f32_e32 v0, v92, v0
	v_add_f32_e32 v0, v93, v0
	v_add_f32_e32 v0, v94, v0
	v_add_f32_e32 v0, v95, v0
	v_cvt_pk_bf16_f32 v2, v88, v89
	v_cvt_pk_bf16_f32 v3, v90, v91
	v_cvt_pk_bf16_f32 v4, v92, v93
	v_cvt_pk_bf16_f32 v5, v94, v95
	s_nop 1
	ds_read_b64 v[88:89], v236 offset:20480
	ds_read_b64 v[90:91], v237 offset:20480
	s_waitcnt lgkmcnt(10)
	v_mfma_f32_32x32x16_bf16 v[64:79], v[84:87], v[2:5], v[64:79]
	ds_read_b64 v[92:93], v236 offset:12288
	ds_read_b64 v[94:95], v237 offset:12288
	v_exp_f32_e32 v96, v96
	v_exp_f32_e32 v97, v97
	s_waitcnt lgkmcnt(10)
	v_mfma_f32_32x32x16_bf16 v[112:127], v[6:9], v[2:5], v[112:127]
	ds_read_b64 v[84:85], v236 offset:16384
	ds_read_b64 v[86:87], v237 offset:16384
	v_exp_f32_e32 v98, v98
	v_exp_f32_e32 v99, v99
	v_add_f32_e32 v0, v96, v0
	v_add_f32_e32 v0, v97, v0
	s_waitcnt lgkmcnt(10)
	v_mfma_f32_32x32x16_bf16 v[48:63], v[10:13], v[2:5], v[48:63]
	ds_read_b64 v[6:7], v238 offset:8192
	ds_read_b64 v[8:9], v239 offset:8192
	v_exp_f32_e32 v100, v100
	v_exp_f32_e32 v101, v101
	v_add_f32_e32 v0, v98, v0
	v_add_f32_e32 v0, v99, v0
	s_waitcnt lgkmcnt(10)
	v_mfma_f32_32x32x16_bf16 v[32:47], v[242:245], v[2:5], v[32:47]
	ds_read_b64 v[10:11], v240 offset:12288
	ds_read_b64 v[12:13], v241 offset:12288
	v_exp_f32_e32 v102, v102
	v_exp_f32_e32 v103, v103
	v_add_f32_e32 v0, v100, v0
	v_add_f32_e32 v0, v101, v0
	v_add_f32_e32 v0, v102, v0
	v_add_f32_e32 v0, v103, v0
	v_cvt_pk_bf16_f32 v2, v96, v97
	v_cvt_pk_bf16_f32 v3, v98, v99
	v_cvt_pk_bf16_f32 v4, v100, v101
	v_cvt_pk_bf16_f32 v5, v102, v103
	s_nop 1
	ds_read_b64 v[242:243], v240 offset:16384
	ds_read_b64 v[244:245], v241 offset:16384
	s_waitcnt lgkmcnt(12)
	v_mfma_f32_32x32x16_bf16 v[64:79], v[80:83], v[2:5], v[64:79]
	ds_read_b64 v[96:97], v240 offset:20480
	ds_read_b64 v[98:99], v241 offset:20480
	v_exp_f32_e32 v104, v104
	v_exp_f32_e32 v105, v105
	s_waitcnt lgkmcnt(12)
	v_mfma_f32_32x32x16_bf16 v[112:127], v[88:91], v[2:5], v[112:127]
	v_exp_f32_e32 v106, v106
	v_exp_f32_e32 v107, v107
	v_add_f32_e32 v0, v104, v0
	v_add_f32_e32 v0, v105, v0
	s_waitcnt lgkmcnt(10)
	v_mfma_f32_32x32x16_bf16 v[48:63], v[92:95], v[2:5], v[48:63]
	v_exp_f32_e32 v108, v108
	v_exp_f32_e32 v109, v109
	v_add_f32_e32 v0, v106, v0
	v_add_f32_e32 v0, v107, v0
	s_waitcnt lgkmcnt(8)
	v_mfma_f32_32x32x16_bf16 v[32:47], v[84:87], v[2:5], v[32:47]
	v_exp_f32_e32 v110, v110
	v_exp_f32_e32 v111, v111
	v_add_f32_e32 v0, v108, v0
	v_add_f32_e32 v0, v109, v0
	v_add_f32_e32 v0, v110, v0
	v_add_f32_e32 v0, v111, v0
	v_cvt_pk_bf16_f32 v2, v104, v105
	v_cvt_pk_bf16_f32 v3, v106, v107
	v_cvt_pk_bf16_f32 v4, v108, v109
	v_cvt_pk_bf16_f32 v5, v110, v111
	s_nop 1
	s_waitcnt lgkmcnt(6)
	v_mfma_f32_32x32x16_bf16 v[64:79], v[6:9], v[2:5], v[64:79]
	s_waitcnt lgkmcnt(4)
	v_mfma_f32_32x32x16_bf16 v[48:63], v[10:13], v[2:5], v[48:63]
	s_waitcnt lgkmcnt(2)
	v_mfma_f32_32x32x16_bf16 v[32:47], v[242:245], v[2:5], v[32:47]
	s_waitcnt lgkmcnt(0)
	v_mfma_f32_32x32x16_bf16 v[112:127], v[96:99], v[2:5], v[112:127]
	v_add_f32_e32 v224, v224, v0
	s_branch .LBB0_1415

.LBB0_1423:
	ds_read_b128 v[2:5], v220
	ds_read_b128 v[6:9], v220 offset:4096
	ds_read_b128 v[10:13], v221
	ds_read_b128 v[244:247], v221 offset:4096
	s_waitcnt lgkmcnt(3)
	v_mfma_f32_32x32x16_bf16 v[80:95], v[2:5], v[160:163], v[16:31]
	v_exp_f32_e32 v128, v128
	v_exp_f32_e32 v129, v129
	ds_read_b128 v[2:5], v222
	s_waitcnt lgkmcnt(3)
	v_mfma_f32_32x32x16_bf16 v[96:111], v[6:9], v[160:163], v[16:31]
	v_exp_f32_e32 v130, v130
	v_exp_f32_e32 v131, v131
	ds_read_b128 v[6:9], v222 offset:4096
	s_waitcnt lgkmcnt(3)
	v_mfma_f32_32x32x16_bf16 v[80:95], v[10:13], v[164:167], v[80:95]
	v_exp_f32_e32 v132, v132
	v_exp_f32_e32 v133, v133
	v_add_f32_e32 v0, 0, v128
	ds_read_b128 v[10:13], v223
	s_waitcnt lgkmcnt(3)
	v_mfma_f32_32x32x16_bf16 v[96:111], v[244:247], v[164:167], v[96:111]
	v_exp_f32_e32 v134, v134
	v_exp_f32_e32 v135, v135
	v_add_f32_e32 v0, v129, v0
	ds_read_b128 v[244:247], v223 offset:4096
	s_waitcnt lgkmcnt(3)
	v_mfma_f32_32x32x16_bf16 v[80:95], v[2:5], v[168:171], v[80:95]
	v_cvt_pk_bf16_f32 v208, v128, v129
	v_add_f32_e32 v0, v130, v0
	v_add_f32_e32 v0, v131, v0
	s_waitcnt lgkmcnt(2)
	v_mfma_f32_32x32x16_bf16 v[96:111], v[6:9], v[168:171], v[96:111]
	v_cvt_pk_bf16_f32 v209, v130, v131
	v_add_f32_e32 v0, v132, v0
	v_add_f32_e32 v0, v133, v0
	ds_read_b64 v[6:7], v226 offset:32768
	ds_read_b64 v[8:9], v227 offset:32768
	s_waitcnt lgkmcnt(3)
	v_mfma_f32_32x32x16_bf16 v[80:95], v[10:13], v[172:175], v[80:95]
	v_cvt_pk_bf16_f32 v210, v132, v133
	v_add_f32_e32 v0, v134, v0
	ds_read_b64 v[10:11], v228 offset:45056
	ds_read_b64 v[12:13], v229 offset:45056
	s_waitcnt lgkmcnt(4)
	v_mfma_f32_32x32x16_bf16 v[96:111], v[244:247], v[172:175], v[96:111]
	v_cvt_pk_bf16_f32 v211, v134, v135
	v_add_f32_e32 v0, v135, v0
	ds_read_b64 v[242:243], v228 offset:36864
	ds_read_b64 v[244:245], v229 offset:36864
	s_or_b64 exec, exec, s[20:21]
	s_and_saveexec_b64 s[20:21], s[4:5]
	ds_read_b64 v[128:129], v228 offset:40960
	ds_read_b64 v[130:131], v229 offset:40960
	ds_read_b64 v[132:133], v230 offset:32768
	ds_read_b64 v[134:135], v231 offset:32768
	s_waitcnt lgkmcnt(8)
	v_mfma_f32_32x32x16_bf16 v[64:79], v[6:9], v[208:211], v[64:79]
	ds_read_b64 v[6:7], v232 offset:45056
	ds_read_b64 v[8:9], v233 offset:45056
	v_exp_f32_e32 v136, v136
	v_exp_f32_e32 v137, v137
	s_waitcnt lgkmcnt(8)
	v_mfma_f32_32x32x16_bf16 v[112:127], v[10:13], v[208:211], v[112:127]
	ds_read_b64 v[10:11], v232 offset:36864
	ds_read_b64 v[12:13], v233 offset:36864
	v_exp_f32_e32 v138, v138
	v_exp_f32_e32 v139, v139
	v_add_f32_e32 v0, v136, v0
	v_add_f32_e32 v0, v137, v0
	s_waitcnt lgkmcnt(8)
	v_mfma_f32_32x32x16_bf16 v[48:63], v[242:245], v[208:211], v[48:63]
	ds_read_b64 v[242:243], v232 offset:40960
	ds_read_b64 v[244:245], v233 offset:40960
	v_exp_f32_e32 v140, v140
	v_exp_f32_e32 v141, v141
	v_add_f32_e32 v0, v138, v0
	v_add_f32_e32 v0, v139, v0
	s_waitcnt lgkmcnt(8)
	v_mfma_f32_32x32x16_bf16 v[32:47], v[128:131], v[208:211], v[32:47]
	ds_read_b64 v[128:129], v234 offset:32768
	ds_read_b64 v[130:131], v235 offset:32768
	v_exp_f32_e32 v142, v142
	v_exp_f32_e32 v143, v143
	v_add_f32_e32 v0, v140, v0
	v_add_f32_e32 v0, v141, v0
	v_add_f32_e32 v0, v142, v0
	v_add_f32_e32 v0, v143, v0
	v_cvt_pk_bf16_f32 v2, v136, v137
	v_cvt_pk_bf16_f32 v3, v138, v139
	v_cvt_pk_bf16_f32 v4, v140, v141
	v_cvt_pk_bf16_f32 v5, v142, v143
	s_nop 1
	ds_read_b64 v[136:137], v236 offset:45056
	ds_read_b64 v[138:139], v237 offset:45056
	s_waitcnt lgkmcnt(10)
	v_mfma_f32_32x32x16_bf16 v[64:79], v[132:135], v[2:5], v[64:79]
	ds_read_b64 v[140:141], v236 offset:36864
	ds_read_b64 v[142:143], v237 offset:36864
	v_exp_f32_e32 v144, v144
	v_exp_f32_e32 v145, v145
	s_waitcnt lgkmcnt(10)
	v_mfma_f32_32x32x16_bf16 v[112:127], v[6:9], v[2:5], v[112:127]
	ds_read_b64 v[132:133], v236 offset:40960
	ds_read_b64 v[134:135], v237 offset:40960
	v_exp_f32_e32 v146, v146
	v_exp_f32_e32 v147, v147
	v_add_f32_e32 v0, v144, v0
	v_add_f32_e32 v0, v145, v0
	s_waitcnt lgkmcnt(10)
	v_mfma_f32_32x32x16_bf16 v[48:63], v[10:13], v[2:5], v[48:63]
	ds_read_b64 v[6:7], v238 offset:32768
	ds_read_b64 v[8:9], v239 offset:32768
	v_exp_f32_e32 v148, v148
	v_exp_f32_e32 v149, v149
	v_add_f32_e32 v0, v146, v0
	v_add_f32_e32 v0, v147, v0
	s_waitcnt lgkmcnt(10)
	v_mfma_f32_32x32x16_bf16 v[32:47], v[242:245], v[2:5], v[32:47]
	ds_read_b64 v[10:11], v240 offset:36864
	ds_read_b64 v[12:13], v241 offset:36864
	v_exp_f32_e32 v150, v150
	v_exp_f32_e32 v151, v151
	v_add_f32_e32 v0, v148, v0
	v_add_f32_e32 v0, v149, v0
	v_add_f32_e32 v0, v150, v0
	v_add_f32_e32 v0, v151, v0
	v_cvt_pk_bf16_f32 v2, v144, v145
	v_cvt_pk_bf16_f32 v3, v146, v147
	v_cvt_pk_bf16_f32 v4, v148, v149
	v_cvt_pk_bf16_f32 v5, v150, v151
	s_nop 1
	ds_read_b64 v[242:243], v240 offset:40960
	ds_read_b64 v[244:245], v241 offset:40960
	s_waitcnt lgkmcnt(12)
	v_mfma_f32_32x32x16_bf16 v[64:79], v[128:131], v[2:5], v[64:79]
	ds_read_b64 v[144:145], v240 offset:45056
	ds_read_b64 v[146:147], v241 offset:45056
	v_exp_f32_e32 v152, v152
	v_exp_f32_e32 v153, v153
	s_waitcnt lgkmcnt(12)
	v_mfma_f32_32x32x16_bf16 v[112:127], v[136:139], v[2:5], v[112:127]
	v_exp_f32_e32 v154, v154
	v_exp_f32_e32 v155, v155
	v_add_f32_e32 v0, v152, v0
	v_add_f32_e32 v0, v153, v0
	s_waitcnt lgkmcnt(10)
	v_mfma_f32_32x32x16_bf16 v[48:63], v[140:143], v[2:5], v[48:63]
	v_exp_f32_e32 v156, v156
	v_exp_f32_e32 v157, v157
	v_add_f32_e32 v0, v154, v0
	v_add_f32_e32 v0, v155, v0
	s_waitcnt lgkmcnt(8)
	v_mfma_f32_32x32x16_bf16 v[32:47], v[132:135], v[2:5], v[32:47]
	v_exp_f32_e32 v158, v158
	v_exp_f32_e32 v159, v159
	v_add_f32_e32 v0, v156, v0
	v_add_f32_e32 v0, v157, v0
	v_add_f32_e32 v0, v158, v0
	v_add_f32_e32 v0, v159, v0
	v_cvt_pk_bf16_f32 v2, v152, v153
	v_cvt_pk_bf16_f32 v3, v154, v155
	v_cvt_pk_bf16_f32 v4, v156, v157
	v_cvt_pk_bf16_f32 v5, v158, v159
	s_nop 1
	s_waitcnt lgkmcnt(6)
	v_mfma_f32_32x32x16_bf16 v[64:79], v[6:9], v[2:5], v[64:79]
	s_waitcnt lgkmcnt(4)
	v_mfma_f32_32x32x16_bf16 v[48:63], v[10:13], v[2:5], v[48:63]
	s_waitcnt lgkmcnt(2)
	v_mfma_f32_32x32x16_bf16 v[32:47], v[242:245], v[2:5], v[32:47]
	s_waitcnt lgkmcnt(0)
	v_mfma_f32_32x32x16_bf16 v[112:127], v[144:147], v[2:5], v[112:127]
	v_add_f32_e32 v224, v0, v224
	s_branch .LBB0_1428
